# NA item loop: next work-queue ticket requested during the last tile (atomic round trip hidden), dequeue with one barrier
# baseline (speedup 1.0000x reference)
; #define LAS __attribute__((address_space(3)))
; DI unsigned xb_add(unsigned* p, unsigned v) { return __hip_atomic_fetch_add(p, v, __ATOMIC_RELAXED, __HIP_MEMORY_SCOPE_AGENT); }
; DI int next_item(unsigned* ctr, volatile LAS int* slot) {
;     __syncthreads();
;     if (threadIdx.x == 0) *slot = (int)xb_add(ctr, 1u);
;     __syncthreads();
; DI void na_block_item(const Params& p, int l, int b, int h, int rp, LAS unsigned char* lds) {
;     ...
;     for (int t = 0; t < ntl; ++t) {
;         const int cur = t % 3;
;         const bool local = t < nloc; const int kr = r0a + t;
;         const int nch = local ? ((kr >= r0w && kr < r0w + 8) ? 1 : 0) : 2;
na0_top:
	s_add_u32 s57, s27, 1
	s_cmp_eq_u32 s57, s31
	s_cbranch_scc0 na0_ntk
	s_and_saveexec_b64 s[0:1], s[24:25]
	s_cbranch_execz na0_ntk2
	v_mov_b32_e32 v252, 1
	v_mov_b32_e32 v229, 0
	s_add_u32 s6, s50, 0x4100
	s_addc_u32 s7, s51, 0
	global_atomic_add v252, v229, v252, s[6:7] sc0
na0_ntk2:
	s_or_b64 exec, exec, s[0:1]
na0_ntk:
	s_add_u32 s70, s27, 1
	s_cmp_ge_u32 s70, s31
	s_cbranch_scc1 na0_nostage
	s_mul_hi_u32 s57, s70, 0x55555556
	s_mul_i32 s57, s57, 3
	s_sub_u32 s57, s70, s57
	s_mul_i32 s63, s57, 0x4400
	s_mul_i32 s57, s57, 0x4800
	v_add_u32_e32 v247, s63, v234
	v_add_u32_e32 v248, s63, v235
	v_add_u32_e32 v249, s57, v236
	v_add_u32_e32 v250, s57, v237
	s_sub_u32 s57, s31, s27
	s_sub_u32 s57, s57, 2
	s_cmp_ge_u32 s57, 3
	s_cbranch_scc1 na0_w12
	s_cmp_eq_u32 s57, 2
	s_cbranch_scc1 na0_w8
	s_cmp_eq_u32 s57, 1
	s_cbranch_scc1 na0_w4
	s_waitcnt vmcnt(0)
	s_branch na0_wd

; #define LAS __attribute__((address_space(3)))
; DI unsigned xb_add(unsigned* p, unsigned v) { return __hip_atomic_fetch_add(p, v, __ATOMIC_RELAXED, __HIP_MEMORY_SCOPE_AGENT); }
; DI void st_bf16x4(bf16_t* p, f32x4 v) { u32x2 w; w.x = cvt_pk_bf16(v[0], v[1]); w.y = cvt_pk_bf16(v[2], v[3]); *(u32x2*)p = w; }
; DI int next_item(unsigned* ctr, volatile LAS int* slot) {
;     __syncthreads();
;     if (threadIdx.x == 0) *slot = (int)xb_add(ctr, 1u);
;     __syncthreads();
;     return *slot;
; DI void na_block_item(const Params& p, int l, int b, int h, int rp, LAS unsigned char* lds) {
;     ...
;     float lt = lsum; lt += __shfl_xor(lt, 16); lt += __shfl_xor(lt, 32);
;     const float inv = 1.f / lt;
;     bf16_t* op = (bf16_t*)(ws + WS_YMIX) + rowq * DM + h * 128 + q4 * 4;
; #pragma unroll
;     for (int d = 0; d < 8; ++d) st_bf16x4(op + d * 16, oacc[d] * inv);
na0_bar:
	s_waitcnt lgkmcnt(0)
	s_barrier
	s_add_u32 s27, s27, 1
	s_cmp_lt_u32 s27, s31
	s_cbranch_scc1 na0_top
	v_mov_b32_e32 v196, v243
	v_mov_b32_e32 v197, v243
	s_nop 1
	v_permlane16_swap_b32_e32 v196, v197
	v_add_f32_e32 v196, v196, v197
	v_mov_b32_e32 v197, v196
	s_nop 1
	v_permlane32_swap_b32_e32 v196, v197
	v_add_f32_e32 v196, v196, v197
	v_rcp_f32_e32 v197, v196
	s_nop 0
	v_fma_f32 v196, -v196, v197, 1.0
	v_fma_f32 v244, v196, v197, v197
	v_pk_mul_f32 v[16:17], v[16:17], v[244:245] op_sel_hi:[1,0]
	v_pk_mul_f32 v[18:19], v[18:19], v[244:245] op_sel_hi:[1,0]
	v_cvt_pk_bf16_f32 v16, v16, v17
	v_cvt_pk_bf16_f32 v17, v18, v19
	global_store_dwordx2 v246, v[16:17], s[10:11] offset:0
	v_pk_mul_f32 v[20:21], v[20:21], v[244:245] op_sel_hi:[1,0]
	v_pk_mul_f32 v[22:23], v[22:23], v[244:245] op_sel_hi:[1,0]
	v_cvt_pk_bf16_f32 v20, v20, v21
	v_cvt_pk_bf16_f32 v21, v22, v23
	global_store_dwordx2 v246, v[20:21], s[10:11] offset:32
	v_pk_mul_f32 v[24:25], v[24:25], v[244:245] op_sel_hi:[1,0]
	v_pk_mul_f32 v[26:27], v[26:27], v[244:245] op_sel_hi:[1,0]
	v_cvt_pk_bf16_f32 v24, v24, v25
	v_cvt_pk_bf16_f32 v25, v26, v27
	global_store_dwordx2 v246, v[24:25], s[10:11] offset:64
	v_pk_mul_f32 v[28:29], v[28:29], v[244:245] op_sel_hi:[1,0]
	v_pk_mul_f32 v[30:31], v[30:31], v[244:245] op_sel_hi:[1,0]
	v_cvt_pk_bf16_f32 v28, v28, v29
	v_cvt_pk_bf16_f32 v29, v30, v31
	global_store_dwordx2 v246, v[28:29], s[10:11] offset:96
	v_pk_mul_f32 v[32:33], v[32:33], v[244:245] op_sel_hi:[1,0]
	v_pk_mul_f32 v[34:35], v[34:35], v[244:245] op_sel_hi:[1,0]
	v_cvt_pk_bf16_f32 v32, v32, v33
	v_cvt_pk_bf16_f32 v33, v34, v35
	global_store_dwordx2 v246, v[32:33], s[10:11] offset:128
	v_pk_mul_f32 v[36:37], v[36:37], v[244:245] op_sel_hi:[1,0]
	v_pk_mul_f32 v[38:39], v[38:39], v[244:245] op_sel_hi:[1,0]
	v_cvt_pk_bf16_f32 v36, v36, v37
	v_cvt_pk_bf16_f32 v37, v38, v39
	global_store_dwordx2 v246, v[36:37], s[10:11] offset:160
	v_pk_mul_f32 v[40:41], v[40:41], v[244:245] op_sel_hi:[1,0]
	v_pk_mul_f32 v[42:43], v[42:43], v[244:245] op_sel_hi:[1,0]
	v_cvt_pk_bf16_f32 v40, v40, v41
	v_cvt_pk_bf16_f32 v41, v42, v43
	global_store_dwordx2 v246, v[40:41], s[10:11] offset:192
	v_pk_mul_f32 v[44:45], v[44:45], v[244:245] op_sel_hi:[1,0]
	v_pk_mul_f32 v[46:47], v[46:47], v[244:245] op_sel_hi:[1,0]
	v_cvt_pk_bf16_f32 v44, v44, v45
	v_cvt_pk_bf16_f32 v45, v46, v47
	global_store_dwordx2 v246, v[44:45], s[10:11] offset:224
	s_and_saveexec_b64 s[0:1], s[24:25]
	s_cbranch_execz na0_nq
	v_mov_b32_e32 v197, 0x22040
	s_waitcnt vmcnt(0)
	ds_write_b32 v197, v252
na0_nq:
	s_or_b64 exec, exec, s[0:1]
	v_mov_b32_e32 v197, 0x22040
	s_waitcnt lgkmcnt(0)
	s_barrier
	ds_read_b32 v196, v197
	s_waitcnt lgkmcnt(0)
	v_readfirstlane_b32 s29, v196
	s_cmp_lt_u32 s29, 0x3b4
	s_cbranch_scc1 na0_item
	s_mov_b32 s28, s29
	v_mov_b32_e32 v133, 0
	s_branch .LBB0_1277

; #define LAS __attribute__((address_space(3)))
; DI unsigned xb_add(unsigned* p, unsigned v) { return __hip_atomic_fetch_add(p, v, __ATOMIC_RELAXED, __HIP_MEMORY_SCOPE_AGENT); }
; DI int next_item(unsigned* ctr, volatile LAS int* slot) {
;     __syncthreads();
;     if (threadIdx.x == 0) *slot = (int)xb_add(ctr, 1u);
;     __syncthreads();
; DI void na_block_item(const Params& p, int l, int b, int h, int rp, LAS unsigned char* lds) {
;     ...
;     for (int t = 0; t < ntl; ++t) {
;         const int cur = t % 3;
;         const bool local = t < nloc; const int kr = r0a + t;
;         const int nch = local ? ((kr >= r0w && kr < r0w + 8) ? 1 : 0) : 2;
na1_top:
	s_add_u32 s57, s27, 1
	s_cmp_eq_u32 s57, s31
	s_cbranch_scc0 na1_ntk
	s_and_saveexec_b64 s[0:1], s[24:25]
	s_cbranch_execz na1_ntk2
	v_mov_b32_e32 v252, 1
	v_mov_b32_e32 v229, 0
	s_add_u32 s6, s50, 0x4200
	s_addc_u32 s7, s51, 0
	global_atomic_add v252, v229, v252, s[6:7] sc0
na1_ntk2:
	s_or_b64 exec, exec, s[0:1]
na1_ntk:
	s_add_u32 s70, s27, 1
	s_cmp_ge_u32 s70, s31
	s_cbranch_scc1 na1_nostage
	s_mul_hi_u32 s57, s70, 0x55555556
	s_mul_i32 s57, s57, 3
	s_sub_u32 s57, s70, s57
	s_mul_i32 s63, s57, 0x4400
	s_mul_i32 s57, s57, 0x4800
	v_add_u32_e32 v247, s63, v234
	v_add_u32_e32 v248, s63, v235
	v_add_u32_e32 v249, s57, v236
	v_add_u32_e32 v250, s57, v237
	s_sub_u32 s57, s31, s27
	s_sub_u32 s57, s57, 2
	s_cmp_ge_u32 s57, 3
	s_cbranch_scc1 na1_w12
	s_cmp_eq_u32 s57, 2
	s_cbranch_scc1 na1_w8
	s_cmp_eq_u32 s57, 1
	s_cbranch_scc1 na1_w4
	s_waitcnt vmcnt(0)
	s_branch na1_wd

; #define LAS __attribute__((address_space(3)))
; DI unsigned xb_add(unsigned* p, unsigned v) { return __hip_atomic_fetch_add(p, v, __ATOMIC_RELAXED, __HIP_MEMORY_SCOPE_AGENT); }
; DI void st_bf16x4(bf16_t* p, f32x4 v) { u32x2 w; w.x = cvt_pk_bf16(v[0], v[1]); w.y = cvt_pk_bf16(v[2], v[3]); *(u32x2*)p = w; }
; DI int next_item(unsigned* ctr, volatile LAS int* slot) {
;     __syncthreads();
;     if (threadIdx.x == 0) *slot = (int)xb_add(ctr, 1u);
;     __syncthreads();
;     return *slot;
; DI void na_block_item(const Params& p, int l, int b, int h, int rp, LAS unsigned char* lds) {
;     ...
;     float lt = lsum; lt += __shfl_xor(lt, 16); lt += __shfl_xor(lt, 32);
;     const float inv = 1.f / lt;
;     bf16_t* op = (bf16_t*)(ws + WS_YMIX) + rowq * DM + h * 128 + q4 * 4;
; #pragma unroll
;     for (int d = 0; d < 8; ++d) st_bf16x4(op + d * 16, oacc[d] * inv);
na1_bar:
	s_waitcnt lgkmcnt(0)
	s_barrier
	s_add_u32 s27, s27, 1
	s_cmp_lt_u32 s27, s31
	s_cbranch_scc1 na1_top
	v_mov_b32_e32 v196, v243
	v_mov_b32_e32 v197, v243
	s_nop 1
	v_permlane16_swap_b32_e32 v196, v197
	v_add_f32_e32 v196, v196, v197
	v_mov_b32_e32 v197, v196
	s_nop 1
	v_permlane32_swap_b32_e32 v196, v197
	v_add_f32_e32 v196, v196, v197
	v_rcp_f32_e32 v197, v196
	s_nop 0
	v_fma_f32 v196, -v196, v197, 1.0
	v_fma_f32 v244, v196, v197, v197
	v_pk_mul_f32 v[16:17], v[16:17], v[244:245] op_sel_hi:[1,0]
	v_pk_mul_f32 v[18:19], v[18:19], v[244:245] op_sel_hi:[1,0]
	v_cvt_pk_bf16_f32 v16, v16, v17
	v_cvt_pk_bf16_f32 v17, v18, v19
	global_store_dwordx2 v246, v[16:17], s[10:11] offset:0
	v_pk_mul_f32 v[20:21], v[20:21], v[244:245] op_sel_hi:[1,0]
	v_pk_mul_f32 v[22:23], v[22:23], v[244:245] op_sel_hi:[1,0]
	v_cvt_pk_bf16_f32 v20, v20, v21
	v_cvt_pk_bf16_f32 v21, v22, v23
	global_store_dwordx2 v246, v[20:21], s[10:11] offset:32
	v_pk_mul_f32 v[24:25], v[24:25], v[244:245] op_sel_hi:[1,0]
	v_pk_mul_f32 v[26:27], v[26:27], v[244:245] op_sel_hi:[1,0]
	v_cvt_pk_bf16_f32 v24, v24, v25
	v_cvt_pk_bf16_f32 v25, v26, v27
	global_store_dwordx2 v246, v[24:25], s[10:11] offset:64
	v_pk_mul_f32 v[28:29], v[28:29], v[244:245] op_sel_hi:[1,0]
	v_pk_mul_f32 v[30:31], v[30:31], v[244:245] op_sel_hi:[1,0]
	v_cvt_pk_bf16_f32 v28, v28, v29
	v_cvt_pk_bf16_f32 v29, v30, v31
	global_store_dwordx2 v246, v[28:29], s[10:11] offset:96
	v_pk_mul_f32 v[32:33], v[32:33], v[244:245] op_sel_hi:[1,0]
	v_pk_mul_f32 v[34:35], v[34:35], v[244:245] op_sel_hi:[1,0]
	v_cvt_pk_bf16_f32 v32, v32, v33
	v_cvt_pk_bf16_f32 v33, v34, v35
	global_store_dwordx2 v246, v[32:33], s[10:11] offset:128
	v_pk_mul_f32 v[36:37], v[36:37], v[244:245] op_sel_hi:[1,0]
	v_pk_mul_f32 v[38:39], v[38:39], v[244:245] op_sel_hi:[1,0]
	v_cvt_pk_bf16_f32 v36, v36, v37
	v_cvt_pk_bf16_f32 v37, v38, v39
	global_store_dwordx2 v246, v[36:37], s[10:11] offset:160
	v_pk_mul_f32 v[40:41], v[40:41], v[244:245] op_sel_hi:[1,0]
	v_pk_mul_f32 v[42:43], v[42:43], v[244:245] op_sel_hi:[1,0]
	v_cvt_pk_bf16_f32 v40, v40, v41
	v_cvt_pk_bf16_f32 v41, v42, v43
	global_store_dwordx2 v246, v[40:41], s[10:11] offset:192
	v_pk_mul_f32 v[44:45], v[44:45], v[244:245] op_sel_hi:[1,0]
	v_pk_mul_f32 v[46:47], v[46:47], v[244:245] op_sel_hi:[1,0]
	v_cvt_pk_bf16_f32 v44, v44, v45
	v_cvt_pk_bf16_f32 v45, v46, v47
	global_store_dwordx2 v246, v[44:45], s[10:11] offset:224
	s_and_saveexec_b64 s[0:1], s[24:25]
	s_cbranch_execz na1_nq
	v_mov_b32_e32 v197, 0x22040
	s_waitcnt vmcnt(0)
	ds_write_b32 v197, v252
na1_nq:
	s_or_b64 exec, exec, s[0:1]
	v_mov_b32_e32 v197, 0x22040
	s_waitcnt lgkmcnt(0)
	s_barrier
	ds_read_b32 v196, v197
	s_waitcnt lgkmcnt(0)
	v_readfirstlane_b32 s29, v196
	s_cmp_lt_u32 s29, 0x360
	s_cbranch_scc1 na1_item
	v_mov_b32_e32 v133, 0
